# P1 epilogue stores back to default policy (pipelined exchange kept)
# baseline (speedup 1.0000x reference)
; #define PG8_LAS __attribute__((address_space(3)))
; __device__ __forceinline__ unsigned cvt_pk_bf16(float lo, float hi) { unsigned r; asm volatile("v_cvt_pk_bf16_f32 %0, %1, %2" : "=v"(r) : "v"(lo), "v"(hi)); return r; }
;     __device__ __forceinline__ void operator()(const f32x4 (&acc)[2][2][4][2], const Unit& u_, int wr, int wc, int fr, int fq) const {
;     ...
;         const int l = fq * 16 + fr; PG8_LAS unsigned char* xl = xl0 + (wr * 4 + wc) * XCHG_WAVE_BYTES;
;         const int rowb = u.pm * BM + wr * 64 + (l >> 2); const int colb = colt + wc * 32 + 8 * (l & 3);
; #pragma unroll
;         for (int ai = 0; ai < 2; ++ai)
; #pragma unroll
;             for (int m = 0; m < 4; ++m) { bf16_t* rowp = base + (size_t)(rowb + ai * HALF + m * 16) * ldc + colb;
; #pragma unroll
;                 for (int bj = 0; bj < 2; ++bj) { const f32x4 v0 = acc[ai][bj][m][0], v1 = acc[ai][bj][m][1];
;                     u32x4 w; w.x = cvt_pk_bf16(v0[0], v0[1]); w.y = cvt_pk_bf16(v0[2], v0[3]); w.z = cvt_pk_bf16(v1[0], v1[1]); w.w = cvt_pk_bf16(v1[2], v1[3]);
;                     *(u32x4*)(rowp + bj * HALF) = xchg_bf16(xl, fr, fq, l, w); } }
.LBB0_263:
	v_lshl_add_u32 v161, s43, 8, v157
	v_add_u32_e32 v152, s2, v156
	v_ashrrev_i32_e32 v153, 31, v152
	v_lshl_add_u64 v[152:153], v[152:153], 1, s[58:59]
	v_mad_u64_u32 v[210:211], s[12:13], s56, v161, 0
	v_lshl_add_u64 v[210:211], v[210:211], 1, v[152:153]
	v_add_u32_e32 v226, 0x10, v161
	v_mad_u64_u32 v[212:213], s[12:13], s56, v226, 0
	v_lshl_add_u64 v[212:213], v[212:213], 1, v[152:153]
	v_add_u32_e32 v226, 0x20, v161
	v_mad_u64_u32 v[214:215], s[12:13], s56, v226, 0
	v_lshl_add_u64 v[214:215], v[214:215], 1, v[152:153]
	v_add_u32_e32 v226, 0x30, v161
	v_mad_u64_u32 v[216:217], s[12:13], s56, v226, 0
	v_lshl_add_u64 v[216:217], v[216:217], 1, v[152:153]
	v_add_u32_e32 v226, 0x80, v161
	v_mad_u64_u32 v[218:219], s[12:13], s56, v226, 0
	v_lshl_add_u64 v[218:219], v[218:219], 1, v[152:153]
	v_add_u32_e32 v226, 0x90, v161
	v_mad_u64_u32 v[220:221], s[12:13], s56, v226, 0
	v_lshl_add_u64 v[220:221], v[220:221], 1, v[152:153]
	v_add_u32_e32 v226, 0xa0, v161
	v_mad_u64_u32 v[222:223], s[12:13], s56, v226, 0
	v_lshl_add_u64 v[222:223], v[222:223], 1, v[152:153]
	v_add_u32_e32 v226, 0xb0, v161
	v_mad_u64_u32 v[224:225], s[12:13], s56, v226, 0
	v_lshl_add_u64 v[224:225], v[224:225], 1, v[152:153]
	s_andn2_b64 vcc, exec, s[0:1]
	s_mov_b64 s[0:1], -1
	v_cvt_pk_bf16_f32 v226, v126, v127
	v_cvt_pk_bf16_f32 v227, v128, v129
	v_cvt_pk_bf16_f32 v228, v122, v123
	v_cvt_pk_bf16_f32 v229, v124, v125
	ds_write_b128 v159, v[226:229]
	ds_read_b128 v[162:165], v160
	v_cvt_pk_bf16_f32 v230, v118, v119
	v_cvt_pk_bf16_f32 v231, v120, v121
	v_cvt_pk_bf16_f32 v232, v110, v111
	v_cvt_pk_bf16_f32 v233, v112, v113
	ds_write_b128 v159, v[230:233]
	ds_read_b128 v[166:169], v160
	v_cvt_pk_bf16_f32 v226, v114, v115
	v_cvt_pk_bf16_f32 v227, v116, v117
	v_cvt_pk_bf16_f32 v228, v106, v107
	v_cvt_pk_bf16_f32 v229, v108, v109
	ds_write_b128 v159, v[226:229]
	ds_read_b128 v[170:173], v160
	v_cvt_pk_bf16_f32 v230, v102, v103
	v_cvt_pk_bf16_f32 v231, v104, v105
	v_cvt_pk_bf16_f32 v232, v94, v95
	v_cvt_pk_bf16_f32 v233, v96, v97
	ds_write_b128 v159, v[230:233]
	ds_read_b128 v[174:177], v160
	s_waitcnt lgkmcnt(6)
	global_store_dwordx4 v[210:211], v[162:165], off
	v_cvt_pk_bf16_f32 v226, v98, v99
	v_cvt_pk_bf16_f32 v227, v100, v101
	v_cvt_pk_bf16_f32 v228, v90, v91
	v_cvt_pk_bf16_f32 v229, v92, v93
	ds_write_b128 v159, v[226:229]
	ds_read_b128 v[178:181], v160
	s_waitcnt lgkmcnt(6)
	global_store_dwordx4 v[210:211], v[166:169], off offset:256
	v_cvt_pk_bf16_f32 v230, v86, v87
	v_cvt_pk_bf16_f32 v231, v88, v89
	v_cvt_pk_bf16_f32 v232, v78, v79
	v_cvt_pk_bf16_f32 v233, v80, v81
	ds_write_b128 v159, v[230:233]
	ds_read_b128 v[182:185], v160
	s_waitcnt lgkmcnt(6)
	global_store_dwordx4 v[212:213], v[170:173], off
	v_cvt_pk_bf16_f32 v226, v82, v83
	v_cvt_pk_bf16_f32 v227, v84, v85
	v_cvt_pk_bf16_f32 v228, v74, v75
	v_cvt_pk_bf16_f32 v229, v76, v77
	ds_write_b128 v159, v[226:229]
	ds_read_b128 v[186:189], v160
	s_waitcnt lgkmcnt(6)
	global_store_dwordx4 v[212:213], v[174:177], off offset:256
	v_cvt_pk_bf16_f32 v230, v70, v71
	v_cvt_pk_bf16_f32 v231, v72, v73
	v_cvt_pk_bf16_f32 v232, v66, v67
	v_cvt_pk_bf16_f32 v233, v68, v69
	ds_write_b128 v159, v[230:233]
	ds_read_b128 v[190:193], v160
	s_waitcnt lgkmcnt(6)
	global_store_dwordx4 v[214:215], v[178:181], off
	v_cvt_pk_bf16_f32 v226, v62, v63
	v_cvt_pk_bf16_f32 v227, v64, v65
	v_cvt_pk_bf16_f32 v228, v58, v59
	v_cvt_pk_bf16_f32 v229, v60, v61
	ds_write_b128 v159, v[226:229]
	ds_read_b128 v[194:197], v160
	s_waitcnt lgkmcnt(6)
	global_store_dwordx4 v[214:215], v[182:185], off offset:256
	v_cvt_pk_bf16_f32 v230, v54, v55
	v_cvt_pk_bf16_f32 v231, v56, v57
	v_cvt_pk_bf16_f32 v232, v46, v47
	v_cvt_pk_bf16_f32 v233, v48, v49
	ds_write_b128 v159, v[230:233]
	ds_read_b128 v[198:201], v160
	s_waitcnt lgkmcnt(6)
	global_store_dwordx4 v[216:217], v[186:189], off
	v_cvt_pk_bf16_f32 v226, v50, v51
	v_cvt_pk_bf16_f32 v227, v52, v53
	v_cvt_pk_bf16_f32 v228, v42, v43
	v_cvt_pk_bf16_f32 v229, v44, v45
	ds_write_b128 v159, v[226:229]
	ds_read_b128 v[202:205], v160
	s_waitcnt lgkmcnt(6)
	global_store_dwordx4 v[216:217], v[190:193], off offset:256
	v_cvt_pk_bf16_f32 v230, v38, v39
	v_cvt_pk_bf16_f32 v231, v40, v41
	v_cvt_pk_bf16_f32 v232, v30, v31
	v_cvt_pk_bf16_f32 v233, v32, v33
	ds_write_b128 v159, v[230:233]
	ds_read_b128 v[206:209], v160
	s_waitcnt lgkmcnt(6)
	global_store_dwordx4 v[218:219], v[194:197], off
	v_cvt_pk_bf16_f32 v226, v34, v35
	v_cvt_pk_bf16_f32 v227, v36, v37
	v_cvt_pk_bf16_f32 v228, v26, v27
	v_cvt_pk_bf16_f32 v229, v28, v29
	ds_write_b128 v159, v[226:229]
	ds_read_b128 v[162:165], v160
	s_waitcnt lgkmcnt(6)
	global_store_dwordx4 v[218:219], v[198:201], off offset:256
	v_cvt_pk_bf16_f32 v230, v22, v23
	v_cvt_pk_bf16_f32 v231, v24, v25
	v_cvt_pk_bf16_f32 v232, v14, v15
	v_cvt_pk_bf16_f32 v233, v16, v17
	ds_write_b128 v159, v[230:233]
	ds_read_b128 v[166:169], v160
	s_waitcnt lgkmcnt(6)
	global_store_dwordx4 v[220:221], v[202:205], off
	v_cvt_pk_bf16_f32 v226, v18, v19
	v_cvt_pk_bf16_f32 v227, v20, v21
	v_cvt_pk_bf16_f32 v228, v10, v11
	v_cvt_pk_bf16_f32 v229, v12, v13
	ds_write_b128 v159, v[226:229]
	ds_read_b128 v[170:173], v160
	s_waitcnt lgkmcnt(6)
	global_store_dwordx4 v[220:221], v[206:209], off offset:256
	v_cvt_pk_bf16_f32 v230, v6, v7
	v_cvt_pk_bf16_f32 v231, v8, v9
	v_cvt_pk_bf16_f32 v232, v2, v3
	v_cvt_pk_bf16_f32 v233, v4, v5
	ds_write_b128 v159, v[230:233]
	ds_read_b128 v[174:177], v160
	s_waitcnt lgkmcnt(6)
	global_store_dwordx4 v[222:223], v[162:165], off
	s_waitcnt lgkmcnt(4)
	global_store_dwordx4 v[222:223], v[166:169], off offset:256
	s_waitcnt lgkmcnt(2)
	global_store_dwordx4 v[224:225], v[170:173], off
	s_waitcnt lgkmcnt(0)
	global_store_dwordx4 v[224:225], v[174:177], off offset:256
	s_cbranch_vccnz .LBB0_244
	s_andn2_b64 vcc, exec, s[4:5]
	s_cbranch_vccnz .LBB0_243
	s_barrier
	s_branch .LBB0_243
